# attention fast step: accumulator-init block kept in registers (rebuilt per key block / after a reference raise), loop-invariant exchange address, identity max/add ops dropped: ~22 fewer VALU issues pe
# speedup vs baseline: 1.0137x; 1.0035x over previous
; __device__ void attn_item(const Params& p, char* lds, int bh, int qi) {
;     ...
;   f32x16 O[2];
; #pragma unroll
;   for (int d = 0; d < 2; ++d)
; #pragma unroll
;     for (int r = 0; r < 16; ++r) O[d][r] = 0.f;
;   float mref = 0.f, lsum = 0.f;
;   bool first = true;
;   const int nsteps = (qi + 1) * 4;
;   const int skey = tid >> 3, sch = tid & 7;
;   u32x4 rk, rv;
;   auto gload = [&](int s) {
;     const int jb = qi - (s >> 2), sub = s & 3, key0 = jb * 256 + sub * 64;
;     rk = *(const u32x4*)(Kg + (size_t)(key0 + skey) * 64 + sch * 8);
;     rv = *(const u32x4*)(Vg + (size_t)skey * SEQ + key0 + sch * 8);
;   };
;   auto swrite = [&](int buf) {
;     *(u32x4*)(Ks + buf * 64 * LD + skey * LD + sch * 8) = rk;
;     u16* vd = Vs + buf * 64 * LD + skey * LD + 16 * (sch >> 1) + 4 * (sch & 1);
;     u32x2 a, b; a.x = rv.x; a.y = rv.y; b.x = rv.z; b.y = rv.w;
;     *(u32x2*)(vd) = a;
;     *(u32x2*)(vd + 8) = b;
;   };
;   gload(0); swrite(0);
;   __syncthreads();
.LBB0_414:
	s_lshl_b32 s5, s22, 18
	s_lshl_b32 s5, s5, 1
	s_add_u32 s18, s10, s5
	v_or_b32_e32 v2, s4, v240
	v_mov_b32_e32 v3, v95
	v_lshl_add_u64 v[18:19], v[96:97], 0, s[6:7]
	s_mov_b32 s5, s7
	s_addc_u32 s19, s11, 0
	v_lshlrev_b64 v[2:3], 7, v[2:3]
	v_mov_b32_e32 v107, v95
	v_lshl_add_u64 v[4:5], s[4:5], 1, v[18:19]
	v_lshl_add_u64 v[2:3], s[18:19], 0, v[2:3]
	v_lshl_add_u64 v[4:5], v[4:5], 0, v[106:107]
	v_lshl_add_u64 v[2:3], v[2:3], 0, v[106:107]
	global_load_dwordx4 v[86:89], v[4:5], off
	global_load_dwordx4 v[82:85], v[2:3], off
	s_mov_b32 s94, 1
	v_cmp_lt_i32_e32 vcc, v156, v157
	s_nop 1
	v_cndmask_b32_e32 v192, v1, v156, vcc
	v_lshlrev_b32_e32 v192, 2, v192
	v_mov_b32_e32 v16, v95
	v_mov_b32_e32 v17, v95
	v_mov_b32_e32 v2, v95
	v_mov_b32_e32 v3, v95
	v_mov_b32_e32 v4, v95
	v_mov_b32_e32 v5, v95
	v_mov_b32_e32 v6, v95
	v_mov_b32_e32 v7, v95
	v_mov_b32_e32 v8, v95
	v_mov_b32_e32 v9, v95
	v_mov_b32_e32 v10, v95
	v_mov_b32_e32 v11, v95
	v_mov_b32_e32 v12, v95
	v_mov_b32_e32 v13, v95
	v_mov_b32_e32 v14, v95
	v_mov_b32_e32 v15, v95
	v_lshl_add_u64 v[108:109], v[18:19], 0, v[106:107]
	v_mov_b64_e32 v[32:33], v[16:17]
	s_lshl_b32 s38, s37, 2
	v_add_u32_e32 v34, 0x4800, v117
	s_mov_b32 s6, 0
	s_mov_b64 s[14:15], -1
	v_mov_b32_e32 v126, 0
	s_mov_b32 s26, 0
	v_mov_b64_e32 v[30:31], v[14:15]
	v_mov_b64_e32 v[28:29], v[12:13]
	v_mov_b64_e32 v[26:27], v[10:11]
	v_mov_b64_e32 v[24:25], v[8:9]
	v_mov_b64_e32 v[22:23], v[6:7]
	v_mov_b64_e32 v[20:21], v[4:5]
	v_mov_b64_e32 v[18:19], v[2:3]
	s_add_i32 s38, s38, 4
	v_lshl_add_u64 v[110:111], s[18:19], 0, v[106:107]
	v_mov_b32_e32 v107, 0
	s_waitcnt vmcnt(1)
	ds_write2_b64 v34, v[86:87], v[88:89] offset1:2
	s_waitcnt vmcnt(0)
	ds_write_b128 v116, v[82:85]
	s_lshl_b32 s20, s37, 8
	s_or_b32 s20, s20, 64
	v_add_u32_e32 v34, s20, v240
	v_ashrrev_i32_e32 v35, 31, v34
	v_lshlrev_b64 v[34:35], 7, v[34:35]
	v_lshl_add_u64 v[34:35], v[110:111], 0, v[34:35]
	s_ashr_i32 s21, s20, 31
	global_load_dwordx4 v[82:85], v[34:35], off
	v_lshl_add_u64 v[34:35], s[20:21], 1, v[108:109]
	global_load_dwordx4 v[86:89], v[34:35], off
	s_waitcnt lgkmcnt(0)
	s_barrier

; __device__ void attn_item(const Params& p, char* lds, int bh, int qi) {
;     ...
;   auto fast_step = [&](auto diag_, int s, int sub, bool sel) {
;     constexpr bool DIAG = decltype(diag_)::value;
;     const u16* ks_ = Ks + (s & 1) * 64 * LD + l31 * LD + 8 * h;
;     const u16* vs_ = Vs + (s & 1) * 64 * LD + l31 * LD + 8 * h;
;     f32x16 cb, S0, S1;
;     {
;       const float cinit = sel ? -mref : -INFINITY;
; #pragma unroll
;       for (int r = 0; r < 16; ++r) cb[r] = cinit;
;     }
;     S0 = __builtin_amdgcn_mfma_f32_32x32x16_bf16(*(const bf16x8*)(ks_), qf[0], cb, 0, 0, 0);
; #pragma unroll
;     for (int ks = 1; ks < 4; ++ks) S0 = __builtin_amdgcn_mfma_f32_32x32x16_bf16(*(const bf16x8*)(ks_ + ks * 16), qf[ks], S0, 0, 0, 0);
;     S1 = __builtin_amdgcn_mfma_f32_32x32x16_bf16(*(const bf16x8*)(ks_ + 32 * LD), qf[0], cb, 0, 0, 0);
; #pragma unroll
;     for (int ks = 1; ks < 4; ++ks) S1 = __builtin_amdgcn_mfma_f32_32x32x16_bf16(*(const bf16x8*)(ks_ + 32 * LD + ks * 16), qf[ks], S1, 0, 0, 0);
;     if constexpr (DIAG) {
;       const int qrel = wave * 32 + l31;
; #pragma unroll
;       for (int r = 0; r < 16; ++r) {
;         const int krel = sub * 64 + rm32(r, h);
;         S0[r] = (krel <= qrel) ? S0[r] : -INFINITY;
;         S1[r] = (krel + 32 <= qrel) ? S1[r] : -INFINITY;
;       }
;     }
;     float mx0 = -INFINITY, mx1 = -INFINITY, ps0 = 0.f, ps1 = 0.f;
; #pragma unroll
;     for (int r = 0; r < 16; r += 2) mx0 = fmaxf(fmaxf(mx0, S0[r]), S0[r + 1]);
; #pragma unroll
;     for (int r = 0; r < 16; ++r) { S0[r] = __builtin_amdgcn_exp2f(S0[r]); ps0 += S0[r]; }
; #pragma unroll
;     for (int sp = 0; sp < 2; ++sp) {
;       u32x4 pw;
;       pw.x = pk2(S0[8 * sp + 0], S0[8 * sp + 1]); pw.y = pk2(S0[8 * sp + 2], S0[8 * sp + 3]);
;       pw.z = pk2(S0[8 * sp + 4], S0[8 * sp + 5]); pw.w = pk2(S0[8 * sp + 6], S0[8 * sp + 7]);
;       const bf16x8 pb = __builtin_bit_cast(bf16x8, pw);
; #pragma unroll
;       for (int d = 0; d < 2; ++d) O[d] = __builtin_amdgcn_mfma_f32_32x32x16_bf16(*(const bf16x8*)(vs_ + d * 32 * LD + sp * 16), pb, O[d], 0, 0, 0);
;     }
; #pragma unroll
;     for (int r = 0; r < 16; r += 2) mx1 = fmaxf(fmaxf(mx1, S1[r]), S1[r + 1]);
; #pragma unroll
;     for (int r = 0; r < 16; ++r) { S1[r] = __builtin_amdgcn_exp2f(S1[r]); ps1 += S1[r]; }
; #pragma unroll
;     for (int sp = 0; sp < 2; ++sp) {
;       u32x4 pw;
.LBB0_436:
	s_and_b32 s26, s6, 64
	s_mulk_i32 s26, 0x90
	v_add_u32_e32 v127, s26, v119
	ds_read_b128 v[90:93], v127 offset:4672
	s_add_i32 s26, s6, 63
	v_cmp_le_u32_e32 vcc, s26, v112
	s_xor_b64 s[22:23], s[22:23], -1
	s_or_b64 s[22:23], s[22:23], vcc
	s_and_saveexec_b64 s[26:27], s[22:23]
	s_xor_b64 s[22:23], exec, s[26:27]
	s_cbranch_execz .LBB0_440
	ds_read_b128 v[128:131], v127
	ds_read_b128 v[132:135], v127 offset:32
	s_and_b32 s95, s39, 3
	s_cmp_eq_u32 s95, 1
	s_cselect_b32 s94, 1, s94
	s_cmp_eq_u32 s94, 0
	s_cbranch_scc1 .Lattn_bias_ok
	v_cndmask_b32_e64 v176, v125, -v107, s[24:25]
	v_mov_b32_e32 v177, v176
	v_mov_b32_e32 v178, v176
	v_mov_b32_e32 v179, v176
	v_mov_b32_e32 v180, v176
	v_mov_b32_e32 v181, v176
	v_mov_b32_e32 v182, v176
	v_mov_b32_e32 v183, v176
	v_mov_b32_e32 v184, v176
	v_mov_b32_e32 v185, v176
	v_mov_b32_e32 v186, v176
	v_mov_b32_e32 v187, v176
	v_mov_b32_e32 v188, v176
	v_mov_b32_e32 v189, v176
	v_mov_b32_e32 v190, v176
	v_mov_b32_e32 v191, v176
	s_mov_b32 s94, 0
	s_nop 1
.Lattn_bias_ok:
	s_waitcnt lgkmcnt(1)
	v_mfma_f32_32x32x16_bf16 v[34:49], v[128:131], v[66:69], v[176:191]
	ds_read_b128 v[128:131], v127 offset:4608
	ds_read_b128 v[136:139], v127 offset:4640
	s_waitcnt lgkmcnt(2)
	v_mfma_f32_32x32x16_bf16 v[34:49], v[132:135], v[70:73], v[34:49]
	s_waitcnt lgkmcnt(1)
	v_mfma_f32_32x32x16_bf16 v[50:65], v[128:131], v[66:69], v[176:191]
	ds_read_b128 v[128:131], v127 offset:64
	ds_read_b128 v[132:135], v127 offset:96
	s_waitcnt lgkmcnt(1)
	v_mfma_f32_32x32x16_bf16 v[34:49], v[128:131], v[74:77], v[34:49]
	ds_read_b128 v[128:131], v127 offset:4704
	v_mfma_f32_32x32x16_bf16 v[50:65], v[136:139], v[70:73], v[50:65]
	s_waitcnt lgkmcnt(1)
	v_mfma_f32_32x32x16_bf16 v[34:49], v[132:135], v[78:81], v[34:49]
	v_mfma_f32_32x32x16_bf16 v[50:65], v[90:93], v[74:77], v[50:65]
	s_nop 10
	v_exp_f32_e32 v140, v34
	v_max3_f32 v34, v34, v35, v36
	v_max3_f32 v34, v34, v37, v38
	v_max3_f32 v34, v34, v39, v40
	v_max3_f32 v34, v34, v41, v42
	s_waitcnt lgkmcnt(0)
	v_mfma_f32_32x32x16_bf16 v[50:65], v[128:131], v[78:81], v[50:65]
	v_exp_f32_e32 v142, v35
	v_exp_f32_e32 v144, v36
	v_exp_f32_e32 v146, v37
	v_exp_f32_e32 v148, v38
	v_exp_f32_e32 v150, v39
	v_exp_f32_e32 v152, v40
	v_exp_f32_e32 v154, v41
	v_max3_f32 v34, v34, v43, v44
	v_exp_f32_e32 v158, v42
	v_exp_f32_e32 v160, v43
	v_exp_f32_e32 v162, v44
	v_exp_f32_e32 v164, v45
	v_max3_f32 v34, v34, v45, v46
	ds_read_b128 v[38:41], v127 offset:18432
	ds_read_b128 v[42:45], v127 offset:23040
	v_exp_f32_e32 v170, v48
	v_max3_f32 v48, v34, v47, v48
	v_cvt_pk_bf16_f32 v34, v140, v142
	v_cvt_pk_bf16_f32 v35, v144, v146
	v_cvt_pk_bf16_f32 v36, v148, v150
	v_cvt_pk_bf16_f32 v37, v152, v154
	v_exp_f32_e32 v166, v46
	v_max3_f32 v46, v50, s34, v51
	s_waitcnt lgkmcnt(1)
	v_mfma_f32_32x32x16_bf16 v[18:33], v[38:41], v[34:37], v[18:33]
	v_max3_f32 v46, v46, v52, v53
	v_exp_f32_e32 v141, v50
	v_max3_f32 v38, v46, v54, v55
	v_exp_f32_e32 v143, v51
	v_exp_f32_e32 v168, v47
	v_exp_f32_e32 v172, v49
	v_max3_f32 v38, v38, v56, v57
	s_waitcnt lgkmcnt(0)
	v_mfma_f32_32x32x16_bf16 v[2:17], v[42:45], v[34:37], v[2:17]
	v_exp_f32_e32 v145, v52
	ds_read_b128 v[128:131], v127 offset:18464
	ds_read_b128 v[132:135], v127 offset:23072
	v_max3_f32 v38, v38, v58, v59
	v_exp_f32_e32 v147, v53
	v_max3_f32 v38, v38, v60, v61
	v_max3_f32 v38, v38, v62, v63
	v_pk_add_f32 v[42:43], v[142:143], v[140:141]
	v_cvt_pk_bf16_f32 v90, v158, v160
	v_cvt_pk_bf16_f32 v91, v162, v164
	v_cvt_pk_bf16_f32 v92, v166, v168
	v_cvt_pk_bf16_f32 v93, v170, v172
	v_max3_f32 v136, v38, v64, v65
	ds_read_b128 v[38:41], v127 offset:18528
	ds_read_b128 v[34:37], v127 offset:18496
	v_pk_add_f32 v[42:43], v[144:145], v[42:43]
	s_waitcnt lgkmcnt(3)
	v_mfma_f32_32x32x16_bf16 v[18:33], v[128:131], v[90:93], v[18:33]
	v_add_f32_e64 v46, v146, v42
	v_add_f32_e64 v47, v147, v43
	ds_read_b128 v[42:45], v127 offset:23104
	v_exp_f32_e32 v149, v54
	v_exp_f32_e32 v151, v55
	v_exp_f32_e32 v153, v56
	v_exp_f32_e32 v155, v57
	v_cvt_pk_bf16_f32 v50, v141, v143
	s_waitcnt lgkmcnt(3)
	v_mfma_f32_32x32x16_bf16 v[2:17], v[132:135], v[90:93], v[2:17]
	v_cvt_pk_bf16_f32 v51, v145, v147
	v_cvt_pk_bf16_f32 v52, v149, v151
	v_cvt_pk_bf16_f32 v53, v153, v155
	v_exp_f32_e32 v159, v58
	v_exp_f32_e32 v161, v59
	v_exp_f32_e32 v163, v60
	v_exp_f32_e32 v165, v61
	s_waitcnt lgkmcnt(1)
	v_mfma_f32_32x32x16_bf16 v[18:33], v[34:37], v[50:53], v[18:33]
	v_exp_f32_e32 v167, v62
	v_exp_f32_e32 v169, v63
	v_exp_f32_e32 v171, v64
	v_exp_f32_e32 v173, v65
	v_pk_add_f32 v[46:47], v[148:149], v[46:47]
	v_cvt_pk_bf16_f32 v34, v159, v161
	v_pk_add_f32 v[46:47], v[150:151], v[46:47]
	s_waitcnt lgkmcnt(0)
	v_mfma_f32_32x32x16_bf16 v[2:17], v[42:45], v[50:53], v[2:17]
	ds_read_b128 v[42:45], v127 offset:23136
	v_add_f32_e64 v46, v152, v46
	v_add_f32_e64 v47, v153, v47
	v_cvt_pk_bf16_f32 v35, v163, v165
	v_cvt_pk_bf16_f32 v36, v167, v169
	v_cvt_pk_bf16_f32 v37, v171, v173
	v_pk_add_f32 v[46:47], v[154:155], v[46:47]
	s_nop 0
	v_mfma_f32_32x32x16_bf16 v[18:33], v[38:41], v[34:37], v[18:33]
	v_add_f32_e64 v38, v158, v46
	v_add_f32_e64 v39, v159, v47
	v_max3_f32 v40, v48, v49, v136
	v_add_f32_e64 v38, v160, v38
	v_add_f32_e64 v39, v161, v39
	v_pk_add_f32 v[38:39], v[162:163], v[38:39]
	s_nop 0
	v_pk_add_f32 v[38:39], v[164:165], v[38:39]
	s_waitcnt lgkmcnt(0)
	v_mfma_f32_32x32x16_bf16 v[2:17], v[42:45], v[34:37], v[2:17]
	v_add_f32_e64 v38, v166, v38
	v_add_f32_e64 v39, v167, v39
	ds_bpermute_b32 v36, v192, v40
	v_pk_add_f32 v[38:39], v[168:169], v[38:39]
	s_nop 0
	v_pk_add_f32 v[34:35], v[170:171], v[38:39]
	s_nop 0
	v_pk_add_f32 v[34:35], v[172:173], v[34:35]
	s_nop 0
	v_add_f32_e32 v34, v34, v35
	v_add_f32_e32 v126, v126, v34
	s_waitcnt lgkmcnt(0)
	v_max_f32_e32 v34, v36, v36
	v_max_f32_e32 v34, v40, v34
	v_cmp_lt_f32_e32 vcc, s35, v34
	s_cbranch_vccz .LBB0_439
	s_nop 0
	s_mov_b32 s94, 1
	v_cndmask_b32_e32 v35, 0, v34, vcc
	v_exp_f32_e64 v34, -v35
	v_add_f32_e32 v107, v107, v35
	v_mul_f32_e32 v126, v126, v34
	v_pk_mul_f32 v[32:33], v[32:33], v[34:35] op_sel_hi:[1,0]
	v_pk_mul_f32 v[30:31], v[30:31], v[34:35] op_sel_hi:[1,0]
	v_pk_mul_f32 v[28:29], v[28:29], v[34:35] op_sel_hi:[1,0]
	v_pk_mul_f32 v[26:27], v[26:27], v[34:35] op_sel_hi:[1,0]
	v_pk_mul_f32 v[24:25], v[24:25], v[34:35] op_sel_hi:[1,0]
	v_pk_mul_f32 v[22:23], v[22:23], v[34:35] op_sel_hi:[1,0]
	v_pk_mul_f32 v[20:21], v[20:21], v[34:35] op_sel_hi:[1,0]
	v_pk_mul_f32 v[18:19], v[18:19], v[34:35] op_sel_hi:[1,0]
	v_pk_mul_f32 v[16:17], v[16:17], v[34:35] op_sel_hi:[1,0]
	v_pk_mul_f32 v[14:15], v[14:15], v[34:35] op_sel_hi:[1,0]
	v_pk_mul_f32 v[12:13], v[12:13], v[34:35] op_sel_hi:[1,0]
	v_pk_mul_f32 v[10:11], v[10:11], v[34:35] op_sel_hi:[1,0]
	v_pk_mul_f32 v[8:9], v[8:9], v[34:35] op_sel_hi:[1,0]
	v_pk_mul_f32 v[6:7], v[6:7], v[34:35] op_sel_hi:[1,0]
	v_pk_mul_f32 v[4:5], v[4:5], v[34:35] op_sel_hi:[1,0]
	v_pk_mul_f32 v[2:3], v[2:3], v[34:35] op_sel_hi:[1,0]
